# local barrier rounds: L1 invalidate hoisted before the generation poll; parallel VSTAT gather
# baseline (speedup 1.0000x reference)
; __device__ __forceinline__ void xcd_barrier(const XcdBarrier& b, int local) {
;     asm volatile("s_waitcnt vmcnt(0)" ::: "memory");
;     __syncthreads();
;     if (threadIdx.x == 0) {
;         unsigned* bar = b.bar;
;         __builtin_amdgcn_s_waitcnt(0);
;         unsigned nloc = b.st[0], nx = b.st[1];
;         if (nloc == 0u) { xcd_barrier_complete(bar, b.x, nloc, nx); b.st[0] = nloc; b.st[1] = nx; }
.LBB0_289:
	s_mov_b64 s[4:5], s[92:93]
	s_mov_b32 s6, 0x20000
	s_mov_b32 s0, 0x20000
	s_add_i32 s0, s0, 0
	v_mov_b32_e32 v0, s0
	ds_read_b32 v0, v0 offset:40
	s_mov_b32 s0, 0x20000
	s_add_i32 s0, s0, 0
	s_waitcnt lgkmcnt(0)
	v_readfirstlane_b32 s15, v0
	v_mov_b32_e32 v0, s0
	ds_read_b32 v0, v0 offset:48
	s_waitcnt vmcnt(0)
	s_waitcnt vmcnt(0) lgkmcnt(0)
	s_barrier
	v_readfirstlane_b32 s100, v0
	s_mov_b64 s[0:1], exec
	v_readlane_b32 s8, v255, 0
	v_readlane_b32 s9, v255, 1
	s_and_b64 s[8:9], s[0:1], s[8:9]
	s_mov_b64 exec, s[8:9]
	s_cbranch_execz .LBB0_343
	s_add_i32 s22, s6, 0
	v_mov_b32_e32 v2, s22
	s_load_dwordx2 s[4:5], s[4:5], 0xa8
	s_waitcnt vmcnt(0) expcnt(0) lgkmcnt(0)
	ds_read_b32 v4, v2 offset:32
	ds_read_b32 v2, v2 offset:36
	s_waitcnt lgkmcnt(1)
	v_cmp_ne_u32_e32 vcc, 0, v4
	s_cbranch_vccnz .LBB0_305
	v_readlane_b32 s6, v255, 2
	v_readlane_b32 s7, v255, 3
	s_load_dwordx2 s[10:11], s[6:7], 0x4
	s_add_u32 s6, s4, 0x1000
	s_addc_u32 s7, s5, 0
	s_add_u32 s8, s4, 0x1100
	s_addc_u32 s9, s5, 0
	s_waitcnt lgkmcnt(0)
	s_mul_i32 s23, s10, s89
	s_add_u32 s10, s4, 0x1200
	s_mul_i32 s23, s23, s11
	s_addc_u32 s11, s5, 0
	s_add_u32 s12, s4, 0x1300
	s_addc_u32 s13, s5, 0
	s_mov_b32 s24, 1
	s_branch .LBB0_293

; __device__ __forceinline__ unsigned xb_ld(unsigned* p)              { return __hip_atomic_load(p, __ATOMIC_RELAXED, __HIP_MEMORY_SCOPE_AGENT); }
; __device__ __forceinline__ unsigned xb_add(unsigned* p, unsigned v) { return __hip_atomic_fetch_add(p, v, __ATOMIC_RELAXED, __HIP_MEMORY_SCOPE_AGENT); }
; #define XB_SPIN(cond, bar) do { unsigned _sp = 0; while (cond) { __builtin_amdgcn_s_sleep(1); \
;     if ((++_sp & 255u) == 0u) { if (xb_ld(&(bar)[XB_TMO])) break; if (_sp > XB_SPIN_CAP) { atomicAdd(&(bar)[XB_TMO], 1u); break; } } } } while (0)
; __device__ __forceinline__ void xcd_barrier(const XcdBarrier& b, int local) {
;     ...
;         const unsigned old = xb_add(&bar[XB_XSUB(b.x)], 1u);
;         const unsigned gen = old / nloc;
;         if (old + 1u == (gen + 1u) * nloc) {
;             if (!local) {
;             __builtin_amdgcn_fence(__ATOMIC_RELEASE, "agent");
;             asm volatile("s_waitcnt vmcnt(0)" ::: "memory");
;             const unsigned og = xb_add(&bar[XB_TOP], 1u);
;             const unsigned tg = og / nx;
;             if (og + 1u == (tg + 1u) * nx) xb_add(&bar[XB_TOPGEN], 1u);
;             else XB_SPIN(xb_ld(&bar[XB_TOPGEN]) == tg, bar);
;             }
;             __builtin_amdgcn_fence(__ATOMIC_ACQUIRE, "agent");
;             xb_add(&bar[XB_XGEN(b.x)], 1u);
;             asm volatile("s_waitcnt vmcnt(0)" ::: "memory");
;         } else {
;             XB_SPIN(xb_ld(&bar[XB_XGEN(b.x)]) == gen, bar);
.LBB0_307:
	s_or_b64 exec, exec, s[8:9]
	v_cvt_f32_u32_e32 v6, v4
	s_waitcnt vmcnt(0)
	v_readfirstlane_b32 s6, v5
	v_sub_u32_e32 v5, 0, v4
	v_rcp_iflag_f32_e32 v6, v6
	v_add_u32_e32 v7, s6, v3
	v_mul_f32_e32 v6, 0x4f7ffffe, v6
	v_cvt_u32_f32_e32 v6, v6
	v_mul_lo_u32 v3, v5, v6
	v_mul_hi_u32 v3, v6, v3
	v_add_u32_e32 v3, v6, v3
	v_mul_hi_u32 v3, v7, v3
	v_mul_lo_u32 v5, v3, v4
	v_sub_u32_e32 v5, v7, v5
	v_add_u32_e32 v6, 1, v3
	v_cmp_ge_u32_e32 vcc, v5, v4
	s_nop 1
	v_cndmask_b32_e32 v3, v3, v6, vcc
	v_sub_u32_e32 v6, v5, v4
	v_cndmask_b32_e32 v5, v5, v6, vcc
	v_add_u32_e32 v6, 1, v3
	v_cmp_ge_u32_e32 vcc, v5, v4
	v_add_u32_e32 v5, 1, v7
	s_nop 0
	v_cndmask_b32_e32 v3, v3, v6, vcc
	v_mul_lo_u32 v6, v4, v3
	v_add_u32_e32 v4, v6, v4
	v_cmp_ne_u32_e32 vcc, v5, v4
	s_and_saveexec_b64 s[6:7], vcc
	s_xor_b64 s[6:7], exec, s[6:7]
	s_cbranch_execz .LBB0_321
	s_add_i32 s80, s15, 0x900
	s_lshl_b64 s[8:9], s[80:81], 2
	s_add_u32 s10, s4, s8
	s_addc_u32 s11, s5, s9
	s_cmp_eq_u32 s100, 0
	s_cbranch_scc1 .Lbi_a9071
	buffer_inv sc1
.Lbi_a9071:
	global_load_dword v0, v1, s[10:11] sc1
	s_waitcnt vmcnt(0)
	v_cmp_eq_u32_e32 vcc, v0, v3
	s_and_saveexec_b64 s[8:9], vcc
	s_cbranch_execz .LBB0_320
	s_mov_b32 s24, 1
	s_mov_b64 s[12:13], 0
	s_branch .LBB0_311

; __device__ __forceinline__ unsigned xb_ld(unsigned* p)              { return __hip_atomic_load(p, __ATOMIC_RELAXED, __HIP_MEMORY_SCOPE_AGENT); }
; __device__ __forceinline__ unsigned xb_add(unsigned* p, unsigned v) { return __hip_atomic_fetch_add(p, v, __ATOMIC_RELAXED, __HIP_MEMORY_SCOPE_AGENT); }
; #define XB_SPIN(cond, bar) do { unsigned _sp = 0; while (cond) { __builtin_amdgcn_s_sleep(1); \
;     if ((++_sp & 255u) == 0u) { if (xb_ld(&(bar)[XB_TMO])) break; if (_sp > XB_SPIN_CAP) { atomicAdd(&(bar)[XB_TMO], 1u); break; } } } } while (0)
; __device__ __forceinline__ void xcd_barrier(const XcdBarrier& b, int local) {
;     ...
;         if (old + 1u == (gen + 1u) * nloc) {
;             if (!local) {
;             __builtin_amdgcn_fence(__ATOMIC_RELEASE, "agent");
;             asm volatile("s_waitcnt vmcnt(0)" ::: "memory");
;             const unsigned og = xb_add(&bar[XB_TOP], 1u);
;             const unsigned tg = og / nx;
;             if (og + 1u == (tg + 1u) * nx) xb_add(&bar[XB_TOPGEN], 1u);
;             else XB_SPIN(xb_ld(&bar[XB_TOPGEN]) == tg, bar);
;             }
;             __builtin_amdgcn_fence(__ATOMIC_ACQUIRE, "agent");
;             xb_add(&bar[XB_XGEN(b.x)], 1u);
;             asm volatile("s_waitcnt vmcnt(0)" ::: "memory");
;         } else {
;             XB_SPIN(xb_ld(&bar[XB_XGEN(b.x)]) == gen, bar);
;             __builtin_amdgcn_fence(__ATOMIC_ACQUIRE, "agent");
;             asm volatile("s_waitcnt vmcnt(0)" ::: "memory");
.LBB0_320:
	s_or_b64 exec, exec, s[8:9]
	s_waitcnt vmcnt(0) lgkmcnt(0)
	s_cmp_lg_u32 s100, 0
	s_cbranch_scc1 .Lbi_b9071
	buffer_inv sc1
.Lbi_b9071:
	s_waitcnt vmcnt(0)
.LBB0_321:
	s_andn2_saveexec_b64 s[6:7], s[6:7]
	s_cbranch_execz .LBB0_343
	v_cmp_ne_u32_e32 vcc, 0, v0
	s_cbranch_vccnz .LBB0_340
	s_mov_b64 s[6:7], exec
	buffer_wbl2 sc1
	s_waitcnt lgkmcnt(0)
	s_waitcnt vmcnt(0)
	v_mbcnt_lo_u32_b32 v0, s6, 0
	v_mbcnt_hi_u32_b32 v0, s7, v0
	v_cmp_eq_u32_e32 vcc, 0, v0
	s_and_saveexec_b64 s[8:9], vcc
	s_cbranch_execz .LBB0_325
	s_bcnt1_i32_b64 s6, s[6:7]
	v_mov_b32_e32 v3, s6
	v_mov_b32_e32 v4, 0x3000
	global_atomic_add v3, v4, v3, s[4:5] offset:1024 sc0

; __device__ __forceinline__ void xcd_barrier(const XcdBarrier& b, int local) {
;     asm volatile("s_waitcnt vmcnt(0)" ::: "memory");
;     __syncthreads();
;     if (threadIdx.x == 0) {
;         unsigned* bar = b.bar;
;         __builtin_amdgcn_s_waitcnt(0);
;         unsigned nloc = b.st[0], nx = b.st[1];
;         if (nloc == 0u) { xcd_barrier_complete(bar, b.x, nloc, nx); b.st[0] = nloc; b.st[1] = nx; }
.LBB0_357:
	s_or_b64 exec, exec, s[0:1]
	s_mov_b64 s[4:5], s[92:93]
	s_mov_b32 s6, 0x20000
	s_mov_b32 s0, 0x20000
	s_add_i32 s0, s0, 0
	v_mov_b32_e32 v0, s0
	ds_read_b32 v0, v0 offset:40
	s_mov_b32 s0, 0x20000
	s_add_i32 s0, s0, 0
	s_waitcnt lgkmcnt(0)
	v_readfirstlane_b32 s15, v0
	v_mov_b32_e32 v0, s0
	ds_read_b32 v0, v0 offset:48
	s_waitcnt vmcnt(0)
	s_waitcnt lgkmcnt(0)
	s_barrier
	v_readfirstlane_b32 s100, v0
	s_mov_b64 s[0:1], exec
	v_readlane_b32 s8, v255, 0
	v_readlane_b32 s9, v255, 1
	s_and_b64 s[8:9], s[0:1], s[8:9]
	s_mov_b64 exec, s[8:9]
	s_cbranch_execz .LBB0_411
	s_add_i32 s22, s6, 0
	v_mov_b32_e32 v2, s22
	s_load_dwordx2 s[4:5], s[4:5], 0xa8
	s_waitcnt vmcnt(0) expcnt(0) lgkmcnt(0)
	ds_read_b32 v4, v2 offset:32
	ds_read_b32 v2, v2 offset:36
	s_waitcnt lgkmcnt(1)
	v_cmp_ne_u32_e32 vcc, 0, v4
	s_cbranch_vccnz .LBB0_373
	v_readlane_b32 s6, v255, 2
	v_readlane_b32 s7, v255, 3
	s_load_dwordx2 s[10:11], s[6:7], 0x4
	s_add_u32 s6, s4, 0x1000
	s_addc_u32 s7, s5, 0
	s_add_u32 s8, s4, 0x1100
	s_addc_u32 s9, s5, 0
	s_waitcnt lgkmcnt(0)
	s_mul_i32 s23, s10, s89
	s_add_u32 s10, s4, 0x1200
	s_mul_i32 s23, s23, s11
	s_addc_u32 s11, s5, 0
	s_add_u32 s12, s4, 0x1300
	s_addc_u32 s13, s5, 0
	s_mov_b32 s24, 1
	s_branch .LBB0_361

; __device__ __forceinline__ unsigned xb_add(unsigned* p, unsigned v) { return __hip_atomic_fetch_add(p, v, __ATOMIC_RELAXED, __HIP_MEMORY_SCOPE_AGENT); }
; __device__ __forceinline__ void xcd_barrier(const XcdBarrier& b, int local) {
;     ...
;         if (old + 1u == (gen + 1u) * nloc) {
;             if (!local) {
;             __builtin_amdgcn_fence(__ATOMIC_RELEASE, "agent");
;             asm volatile("s_waitcnt vmcnt(0)" ::: "memory");
;             const unsigned og = xb_add(&bar[XB_TOP], 1u);
;             const unsigned tg = og / nx;
;             if (og + 1u == (tg + 1u) * nx) xb_add(&bar[XB_TOPGEN], 1u);
.Lbi_b10125:
	s_waitcnt vmcnt(0)
.LBB0_389:
	s_andn2_saveexec_b64 s[6:7], s[6:7]
	s_cbranch_execz .LBB0_411
	v_cmp_ne_u32_e32 vcc, 0, v0
	s_cbranch_vccnz .LBB0_408
	s_mov_b64 s[6:7], exec
	buffer_wbl2 sc1
	s_waitcnt lgkmcnt(0)
	s_waitcnt vmcnt(0)
	v_mbcnt_lo_u32_b32 v0, s6, 0
	v_mbcnt_hi_u32_b32 v0, s7, v0
	v_cmp_eq_u32_e32 vcc, 0, v0
	s_and_saveexec_b64 s[8:9], vcc
	s_cbranch_execz .LBB0_393
	s_bcnt1_i32_b64 s6, s[6:7]
	v_mov_b32_e32 v3, s6
	v_mov_b32_e32 v4, 0x3000
	global_atomic_add v3, v4, v3, s[4:5] offset:1024 sc0

; __device__ __forceinline__ void xcd_barrier(const XcdBarrier& b, int local) {
;     asm volatile("s_waitcnt vmcnt(0)" ::: "memory");
;     __syncthreads();
;     if (threadIdx.x == 0) {
;         unsigned* bar = b.bar;
;         __builtin_amdgcn_s_waitcnt(0);
;         unsigned nloc = b.st[0], nx = b.st[1];
;         if (nloc == 0u) { xcd_barrier_complete(bar, b.x, nloc, nx); b.st[0] = nloc; b.st[1] = nx; }
.LBB0_497:
	s_mov_b64 s[4:5], s[92:93]
	s_mov_b32 s6, 0x20000
	s_mov_b32 s0, 0x20000
	s_add_i32 s0, s0, 0
	v_mov_b32_e32 v0, s0
	ds_read_b32 v0, v0 offset:40
	s_mov_b32 s0, 0x20000
	s_add_i32 s0, s0, 0
	s_waitcnt lgkmcnt(0)
	v_readfirstlane_b32 s15, v0
	v_mov_b32_e32 v0, s0
	ds_read_b32 v0, v0 offset:48
	s_waitcnt vmcnt(0)
	s_waitcnt lgkmcnt(0)
	s_barrier
	v_readfirstlane_b32 s100, v0
	s_mov_b64 s[0:1], exec
	v_readlane_b32 s8, v255, 0
	v_readlane_b32 s9, v255, 1
	s_and_b64 s[8:9], s[0:1], s[8:9]
	s_mov_b64 exec, s[8:9]
	s_cbranch_execz .LBB0_551
	s_add_i32 s22, s6, 0
	v_mov_b32_e32 v2, s22
	s_load_dwordx2 s[4:5], s[4:5], 0xa8
	s_waitcnt vmcnt(0) expcnt(0) lgkmcnt(0)
	ds_read_b32 v4, v2 offset:32
	ds_read_b32 v2, v2 offset:36
	s_waitcnt lgkmcnt(1)
	v_cmp_ne_u32_e32 vcc, 0, v4
	s_cbranch_vccnz .LBB0_513
	v_readlane_b32 s6, v255, 2
	v_readlane_b32 s7, v255, 3
	s_load_dwordx2 s[10:11], s[6:7], 0x4
	s_add_u32 s6, s4, 0x1000
	s_addc_u32 s7, s5, 0
	s_add_u32 s8, s4, 0x1100
	s_addc_u32 s9, s5, 0
	s_waitcnt lgkmcnt(0)
	s_mul_i32 s23, s10, s89
	s_add_u32 s10, s4, 0x1200
	s_mul_i32 s23, s23, s11
	s_addc_u32 s11, s5, 0
	s_add_u32 s12, s4, 0x1300
	s_addc_u32 s13, s5, 0
	s_mov_b32 s24, 1
	s_branch .LBB0_501

; __device__ __forceinline__ unsigned xb_add(unsigned* p, unsigned v) { return __hip_atomic_fetch_add(p, v, __ATOMIC_RELAXED, __HIP_MEMORY_SCOPE_AGENT); }
; __device__ __forceinline__ void xcd_barrier(const XcdBarrier& b, int local) {
;     ...
;         if (old + 1u == (gen + 1u) * nloc) {
;             if (!local) {
;             __builtin_amdgcn_fence(__ATOMIC_RELEASE, "agent");
;             asm volatile("s_waitcnt vmcnt(0)" ::: "memory");
;             const unsigned og = xb_add(&bar[XB_TOP], 1u);
;             const unsigned tg = og / nx;
;             if (og + 1u == (tg + 1u) * nx) xb_add(&bar[XB_TOPGEN], 1u);
.Lbi_b13660:
	s_waitcnt vmcnt(0)
.LBB0_529:
	s_andn2_saveexec_b64 s[6:7], s[6:7]
	s_cbranch_execz .LBB0_551
	v_cmp_ne_u32_e32 vcc, 0, v0
	s_cbranch_vccnz .LBB0_548
	s_mov_b64 s[6:7], exec
	buffer_wbl2 sc1
	s_waitcnt lgkmcnt(0)
	s_waitcnt vmcnt(0)
	v_mbcnt_lo_u32_b32 v0, s6, 0
	v_mbcnt_hi_u32_b32 v0, s7, v0
	v_cmp_eq_u32_e32 vcc, 0, v0
	s_and_saveexec_b64 s[8:9], vcc
	s_cbranch_execz .LBB0_533
	s_bcnt1_i32_b64 s6, s[6:7]
	v_mov_b32_e32 v3, s6
	v_mov_b32_e32 v4, 0x3000
	global_atomic_add v3, v4, v3, s[4:5] offset:1024 sc0

; __device__ __forceinline__ unsigned xb_add(unsigned* p, unsigned v) { return __hip_atomic_fetch_add(p, v, __ATOMIC_RELAXED, __HIP_MEMORY_SCOPE_AGENT); }
; __device__ __forceinline__ void xcd_barrier(const XcdBarrier& b, int local) {
;     ...
;         if (old + 1u == (gen + 1u) * nloc) {
;             if (!local) {
;             __builtin_amdgcn_fence(__ATOMIC_RELEASE, "agent");
;             asm volatile("s_waitcnt vmcnt(0)" ::: "memory");
;             const unsigned og = xb_add(&bar[XB_TOP], 1u);
;             const unsigned tg = og / nx;
;             if (og + 1u == (tg + 1u) * nx) xb_add(&bar[XB_TOPGEN], 1u);
.Lbi_b15705:
	s_waitcnt vmcnt(0)
.LBB0_611:
	s_andn2_saveexec_b64 s[6:7], s[6:7]
	s_cbranch_execz .LBB0_633
	v_cmp_ne_u32_e32 vcc, 0, v0
	s_cbranch_vccnz .LBB0_630
	s_mov_b64 s[6:7], exec
	buffer_wbl2 sc1
	s_waitcnt lgkmcnt(0)
	s_waitcnt vmcnt(0)
	v_mbcnt_lo_u32_b32 v0, s6, 0
	v_mbcnt_hi_u32_b32 v0, s7, v0
	v_cmp_eq_u32_e32 vcc, 0, v0
	s_and_saveexec_b64 s[8:9], vcc
	s_cbranch_execz .LBB0_615
	s_bcnt1_i32_b64 s6, s[6:7]
	v_mov_b32_e32 v3, s6
	v_mov_b32_e32 v4, 0x3000
	global_atomic_add v3, v4, v3, s[4:5] offset:1024 sc0

; __device__ __forceinline__ void xcd_barrier(const XcdBarrier& b, int local) {
;     asm volatile("s_waitcnt vmcnt(0)" ::: "memory");
;     __syncthreads();
;     if (threadIdx.x == 0) {
;         unsigned* bar = b.bar;
;         __builtin_amdgcn_s_waitcnt(0);
;         unsigned nloc = b.st[0], nx = b.st[1];
;         if (nloc == 0u) { xcd_barrier_complete(bar, b.x, nloc, nx); b.st[0] = nloc; b.st[1] = nx; }
.LBB0_655:
	s_or_b64 exec, exec, s[8:9]
	s_mov_b64 s[4:5], s[92:93]
	s_mov_b32 s6, 0x20000
	s_mov_b32 s0, 0x20000
	s_add_i32 s0, s0, 0
	v_mov_b32_e32 v0, s0
	ds_read_b32 v0, v0 offset:40
	s_mov_b32 s0, 0x20000
	s_add_i32 s0, s0, 0
	s_waitcnt lgkmcnt(0)
	v_readfirstlane_b32 s15, v0
	v_mov_b32_e32 v0, s0
	ds_read_b32 v0, v0 offset:48
	s_waitcnt vmcnt(0)
	s_waitcnt lgkmcnt(0)
	s_barrier
	v_readfirstlane_b32 s100, v0
	s_mov_b64 s[0:1], exec
	v_readlane_b32 s8, v255, 0
	v_readlane_b32 s9, v255, 1
	s_and_b64 s[8:9], s[0:1], s[8:9]
	s_mov_b64 exec, s[8:9]
	s_cbranch_execz .LBB0_709
	s_add_i32 s22, s6, 0
	v_mov_b32_e32 v2, s22
	s_load_dwordx2 s[4:5], s[4:5], 0xa8
	s_waitcnt vmcnt(0) expcnt(0) lgkmcnt(0)
	ds_read_b32 v4, v2 offset:32
	ds_read_b32 v2, v2 offset:36
	s_waitcnt lgkmcnt(1)
	v_cmp_ne_u32_e32 vcc, 0, v4
	s_cbranch_vccnz .LBB0_671
	v_readlane_b32 s6, v255, 2
	v_readlane_b32 s7, v255, 3
	s_load_dwordx2 s[10:11], s[6:7], 0x4
	s_add_u32 s6, s4, 0x1000
	s_addc_u32 s7, s5, 0
	s_add_u32 s8, s4, 0x1100
	s_addc_u32 s9, s5, 0
	s_waitcnt lgkmcnt(0)
	s_mul_i32 s23, s10, s89
	s_add_u32 s10, s4, 0x1200
	s_mul_i32 s23, s23, s11
	s_addc_u32 s11, s5, 0
	s_add_u32 s12, s4, 0x1300
	s_addc_u32 s13, s5, 0
	s_mov_b32 s24, 1
	s_branch .LBB0_659

; __device__ __forceinline__ unsigned xb_add(unsigned* p, unsigned v) { return __hip_atomic_fetch_add(p, v, __ATOMIC_RELAXED, __HIP_MEMORY_SCOPE_AGENT); }
; __device__ __forceinline__ void xcd_barrier(const XcdBarrier& b, int local) {
;     ...
;         if (old + 1u == (gen + 1u) * nloc) {
;             if (!local) {
;             __builtin_amdgcn_fence(__ATOMIC_RELEASE, "agent");
;             asm volatile("s_waitcnt vmcnt(0)" ::: "memory");
;             const unsigned og = xb_add(&bar[XB_TOP], 1u);
;             const unsigned tg = og / nx;
;             if (og + 1u == (tg + 1u) * nx) xb_add(&bar[XB_TOPGEN], 1u);
.Lbi_b17327:
	s_waitcnt vmcnt(0)
.LBB0_687:
	s_andn2_saveexec_b64 s[6:7], s[6:7]
	s_cbranch_execz .LBB0_709
	v_cmp_ne_u32_e32 vcc, 0, v0
	s_cbranch_vccnz .LBB0_706
	s_mov_b64 s[6:7], exec
	buffer_wbl2 sc1
	s_waitcnt lgkmcnt(0)
	s_waitcnt vmcnt(0)
	v_mbcnt_lo_u32_b32 v0, s6, 0
	v_mbcnt_hi_u32_b32 v0, s7, v0
	v_cmp_eq_u32_e32 vcc, 0, v0
	s_and_saveexec_b64 s[8:9], vcc
	s_cbranch_execz .LBB0_691
	s_bcnt1_i32_b64 s6, s[6:7]
	v_mov_b32_e32 v3, s6
	v_mov_b32_e32 v4, 0x3000
	global_atomic_add v3, v4, v3, s[4:5] offset:1024 sc0

; __device__ __forceinline__ void xcd_barrier(const XcdBarrier& b, int local) {
;     asm volatile("s_waitcnt vmcnt(0)" ::: "memory");
;     __syncthreads();
;     if (threadIdx.x == 0) {
;         unsigned* bar = b.bar;
;         __builtin_amdgcn_s_waitcnt(0);
;         unsigned nloc = b.st[0], nx = b.st[1];
;         if (nloc == 0u) { xcd_barrier_complete(bar, b.x, nloc, nx); b.st[0] = nloc; b.st[1] = nx; }
.LBB0_807:
	s_waitcnt lgkmcnt(0)
	s_mov_b64 s[4:5], s[92:93]
	s_mov_b32 s6, 0x20000
	s_mov_b32 s0, 0x20000
	s_add_i32 s0, s0, 0
	v_mov_b32_e32 v0, s0
	ds_read_b32 v0, v0 offset:40
	s_mov_b32 s0, 0x20000
	s_add_i32 s0, s0, 0
	s_waitcnt lgkmcnt(0)
	v_readfirstlane_b32 s15, v0
	v_mov_b32_e32 v0, s0
	ds_read_b32 v0, v0 offset:48
	s_waitcnt vmcnt(0)
	s_waitcnt vmcnt(0) lgkmcnt(0)
	s_barrier
	v_readfirstlane_b32 s100, v0
	s_mov_b64 s[0:1], exec
	v_readlane_b32 s8, v255, 0
	v_readlane_b32 s9, v255, 1
	s_and_b64 s[8:9], s[0:1], s[8:9]
	s_mov_b64 exec, s[8:9]
	s_cbranch_execz .LBB0_861
	s_add_i32 s22, s6, 0
	v_mov_b32_e32 v2, s22
	s_load_dwordx2 s[4:5], s[4:5], 0xa8
	s_waitcnt vmcnt(0) expcnt(0) lgkmcnt(0)
	ds_read_b32 v4, v2 offset:32
	ds_read_b32 v2, v2 offset:36
	s_waitcnt lgkmcnt(1)
	v_cmp_ne_u32_e32 vcc, 0, v4
	s_cbranch_vccnz .LBB0_823
	v_readlane_b32 s6, v255, 2
	v_readlane_b32 s7, v255, 3
	s_load_dwordx2 s[10:11], s[6:7], 0x4
	s_add_u32 s6, s4, 0x1000
	s_addc_u32 s7, s5, 0
	s_add_u32 s8, s4, 0x1100
	s_addc_u32 s9, s5, 0
	s_waitcnt lgkmcnt(0)
	s_mul_i32 s23, s10, s89
	s_add_u32 s10, s4, 0x1200
	s_mul_i32 s23, s23, s11
	s_addc_u32 s11, s5, 0
	s_add_u32 s12, s4, 0x1300
	s_addc_u32 s13, s5, 0
	s_mov_b32 s24, 1
	s_branch .LBB0_811

; __device__ __forceinline__ unsigned xb_add(unsigned* p, unsigned v) { return __hip_atomic_fetch_add(p, v, __ATOMIC_RELAXED, __HIP_MEMORY_SCOPE_AGENT); }
; __device__ __forceinline__ void xcd_barrier(const XcdBarrier& b, int local) {
;     ...
;         if (old + 1u == (gen + 1u) * nloc) {
;             if (!local) {
;             __builtin_amdgcn_fence(__ATOMIC_RELEASE, "agent");
;             asm volatile("s_waitcnt vmcnt(0)" ::: "memory");
;             const unsigned og = xb_add(&bar[XB_TOP], 1u);
;             const unsigned tg = og / nx;
;             if (og + 1u == (tg + 1u) * nx) xb_add(&bar[XB_TOPGEN], 1u);
.Lbi_b24128:
	s_waitcnt vmcnt(0)
.LBB0_839:
	s_andn2_saveexec_b64 s[6:7], s[6:7]
	s_cbranch_execz .LBB0_861
	v_cmp_ne_u32_e32 vcc, 0, v0
	s_cbranch_vccnz .LBB0_858
	s_mov_b64 s[6:7], exec
	buffer_wbl2 sc1
	s_waitcnt lgkmcnt(0)
	s_waitcnt vmcnt(0)
	v_mbcnt_lo_u32_b32 v0, s6, 0
	v_mbcnt_hi_u32_b32 v0, s7, v0
	v_cmp_eq_u32_e32 vcc, 0, v0
	s_and_saveexec_b64 s[8:9], vcc
	s_cbranch_execz .LBB0_843
	s_bcnt1_i32_b64 s6, s[6:7]
	v_mov_b32_e32 v3, s6
	v_mov_b32_e32 v4, 0x3000
	global_atomic_add v3, v4, v3, s[4:5] offset:1024 sc0

; __device__ __forceinline__ void spatial_phase(int j, const bf16_t* UG, bf16_t* Y, const bf16_t* Vt, LAS unsigned char* lds, int sw, View vw) {
;     ...
;         __syncthreads();
;         if (tid < 128) { float s = 0.f, q = 0.f;
; #pragma unroll
;             for (int p = 0; p < 16; ++p) { const f32x2 v = VSTAT[(size_t)p * M + tok0 + tid]; s += v[0]; q += v[1]; }
;             const float mu = s * (1.0f / E), var = q * (1.0f / E) - mu * mu;
;             MU[tid] = mu; RS[tid] = 1.0f / sqrtf(var + EPS); }
.LBB0_870:
	s_barrier
	s_mov_b64 s[92:93], exec
	v_readlane_b32 s76, v255, 28
	v_readlane_b32 s77, v255, 29
	s_and_b64 s[76:77], s[92:93], s[76:77]
	s_mov_b64 exec, s[76:77]
	s_cbranch_execz .LBB0_872
	s_lshl_b32 s76, s94, 7
	s_ashr_i32 s77, s76, 31
	v_lshl_add_u64 v[2:3], s[76:77], 3, v[138:139]
	global_load_dwordx2 v[186:187], v[2:3], off
	v_add_co_u32_e32 v4, vcc, 0x40000, v2
	s_nop 1
	v_addc_co_u32_e32 v5, vcc, 0, v3, vcc
	global_load_dwordx2 v[188:189], v[4:5], off
	v_add_co_u32_e32 v4, vcc, 0x80000, v2
	s_nop 1
	v_addc_co_u32_e32 v5, vcc, 0, v3, vcc
	global_load_dwordx2 v[190:191], v[4:5], off
	v_add_co_u32_e32 v4, vcc, 0xc0000, v2
	s_nop 1
	v_addc_co_u32_e32 v5, vcc, 0, v3, vcc
	global_load_dwordx2 v[192:193], v[4:5], off
	v_add_co_u32_e32 v4, vcc, 0x100000, v2
	s_nop 1
	v_addc_co_u32_e32 v5, vcc, 0, v3, vcc
	global_load_dwordx2 v[194:195], v[4:5], off
	v_add_co_u32_e32 v4, vcc, 0x140000, v2
	s_nop 1
	v_addc_co_u32_e32 v5, vcc, 0, v3, vcc
	global_load_dwordx2 v[196:197], v[4:5], off
	v_add_co_u32_e32 v4, vcc, 0x180000, v2
	s_nop 1
	v_addc_co_u32_e32 v5, vcc, 0, v3, vcc
	global_load_dwordx2 v[198:199], v[4:5], off
	v_add_co_u32_e32 v4, vcc, 0x1c0000, v2
	s_nop 1
	v_addc_co_u32_e32 v5, vcc, 0, v3, vcc
	global_load_dwordx2 v[200:201], v[4:5], off
	v_add_co_u32_e32 v4, vcc, 0x200000, v2
	s_nop 1
	v_addc_co_u32_e32 v5, vcc, 0, v3, vcc
	global_load_dwordx2 v[202:203], v[4:5], off
	v_add_co_u32_e32 v4, vcc, 0x240000, v2
	s_nop 1
	v_addc_co_u32_e32 v5, vcc, 0, v3, vcc
	global_load_dwordx2 v[204:205], v[4:5], off
	v_add_co_u32_e32 v4, vcc, 0x280000, v2
	s_nop 1
	v_addc_co_u32_e32 v5, vcc, 0, v3, vcc
	global_load_dwordx2 v[206:207], v[4:5], off
	v_add_co_u32_e32 v4, vcc, 0x2c0000, v2
	s_nop 1
	v_addc_co_u32_e32 v5, vcc, 0, v3, vcc
	global_load_dwordx2 v[208:209], v[4:5], off
	v_add_co_u32_e32 v4, vcc, 0x300000, v2
	s_nop 1
	v_addc_co_u32_e32 v5, vcc, 0, v3, vcc
	global_load_dwordx2 v[210:211], v[4:5], off
	v_add_co_u32_e32 v4, vcc, 0x340000, v2
	s_nop 1
	v_addc_co_u32_e32 v5, vcc, 0, v3, vcc
	global_load_dwordx2 v[212:213], v[4:5], off
	v_add_co_u32_e32 v4, vcc, 0x380000, v2
	s_nop 1
	v_addc_co_u32_e32 v5, vcc, 0, v3, vcc
	global_load_dwordx2 v[214:215], v[4:5], off
	v_add_co_u32_e32 v4, vcc, 0x3c0000, v2
	s_nop 1
	v_addc_co_u32_e32 v5, vcc, 0, v3, vcc
	global_load_dwordx2 v[216:217], v[4:5], off
	s_mov_b32 s5, 0x3a000000
	s_waitcnt vmcnt(0)
	v_add_f32_e32 v6, 0, v186
	v_add_f32_e32 v7, 0, v187
	v_add_f32_e32 v6, v6, v188
	v_add_f32_e32 v7, v7, v189
	v_add_f32_e32 v6, v6, v190
	v_add_f32_e32 v7, v7, v191
	v_add_f32_e32 v6, v6, v192
	v_add_f32_e32 v7, v7, v193
	v_add_f32_e32 v6, v6, v194
	v_add_f32_e32 v7, v7, v195
	v_add_f32_e32 v6, v6, v196
	v_add_f32_e32 v7, v7, v197
	v_add_f32_e32 v6, v6, v198
	v_add_f32_e32 v7, v7, v199
	v_add_f32_e32 v6, v6, v200
	v_add_f32_e32 v7, v7, v201
	v_add_f32_e32 v6, v6, v202
	v_add_f32_e32 v7, v7, v203
	v_add_f32_e32 v6, v6, v204
	v_add_f32_e32 v7, v7, v205
	v_add_f32_e32 v6, v6, v206
	v_add_f32_e32 v7, v7, v207
	v_add_f32_e32 v6, v6, v208
	v_add_f32_e32 v7, v7, v209
	v_add_f32_e32 v6, v6, v210
	v_add_f32_e32 v7, v7, v211
	v_add_f32_e32 v6, v6, v212
	v_add_f32_e32 v7, v7, v213
	v_add_f32_e32 v4, v6, v214
	v_add_f32_e32 v5, v7, v215
	v_add_f32_e32 v2, v4, v216
	v_mul_f32_e32 v2, 0x3a000000, v2
	v_add_f32_e32 v3, v5, v217
	v_mul_f32_e32 v4, v2, v2
	v_fma_f32 v3, v3, s5, -v4
	ds_write_b32 v171, v2
	v_add_f32_e32 v2, 0x358637bd, v3
	s_mov_b32 s5, 0xf800000
	v_cmp_gt_f32_e32 vcc, s5, v2
	v_mul_f32_e32 v3, 0x4f800000, v2
	s_nop 0
	v_cndmask_b32_e32 v2, v2, v3, vcc
	v_sqrt_f32_e32 v3, v2
	s_nop 0
	v_add_u32_e32 v4, -1, v3
	v_fma_f32 v5, -v4, v3, v2
	v_cmp_ge_f32_e64 s[76:77], 0, v5
	v_add_u32_e32 v5, 1, v3
	s_nop 0
	v_cndmask_b32_e64 v4, v3, v4, s[76:77]
	v_fma_f32 v3, -v5, v3, v2
	v_cmp_lt_f32_e64 s[76:77], 0, v3
	s_nop 1
	v_cndmask_b32_e64 v3, v4, v5, s[76:77]
	v_mul_f32_e32 v4, 0x37800000, v3
	v_cndmask_b32_e32 v3, v3, v4, vcc
	v_cmp_class_f32_e32 vcc, v2, v253
	s_nop 1
	v_cndmask_b32_e32 v2, v3, v2, vcc
	v_div_scale_f32 v3, s[76:77], v2, v2, 1.0
	v_rcp_f32_e32 v4, v3
	s_nop 0
	v_fma_f32 v5, -v3, v4, 1.0
	v_fmac_f32_e32 v4, v5, v4
	v_div_scale_f32 v5, vcc, 1.0, v2, 1.0
	v_mul_f32_e32 v6, v5, v4
	v_fma_f32 v7, -v3, v6, v5
	v_fmac_f32_e32 v6, v7, v4
	v_fma_f32 v3, -v3, v6, v5
	v_div_fmas_f32 v3, v3, v4, v6
	v_div_fixup_f32 v2, v3, v2, 1.0
	ds_write_b32 v172, v2

; __device__ __forceinline__ void xcd_barrier(const XcdBarrier& b, int local) {
;     asm volatile("s_waitcnt vmcnt(0)" ::: "memory");
;     __syncthreads();
;     if (threadIdx.x == 0) {
;         unsigned* bar = b.bar;
;         __builtin_amdgcn_s_waitcnt(0);
;         unsigned nloc = b.st[0], nx = b.st[1];
;         if (nloc == 0u) { xcd_barrier_complete(bar, b.x, nloc, nx); b.st[0] = nloc; b.st[1] = nx; }
.LBB0_1011:
	s_mov_b64 s[4:5], s[92:93]
	s_mov_b32 s6, 0x20000
	s_mov_b32 s0, 0x20000
	s_barrier
	s_add_i32 s0, s0, 0
	v_mov_b32_e32 v0, s0
	ds_read_b32 v0, v0 offset:40
	s_mov_b32 s0, 0x20000
	s_add_i32 s0, s0, 0
	s_waitcnt lgkmcnt(0)
	v_readfirstlane_b32 s20, v0
	v_mov_b32_e32 v0, s0
	ds_read_b32 v0, v0 offset:48
	s_waitcnt vmcnt(0)
	s_waitcnt lgkmcnt(0)
	s_barrier
	v_readfirstlane_b32 s100, v0
	s_mov_b64 s[0:1], exec
	v_readlane_b32 s8, v255, 0
	v_readlane_b32 s9, v255, 1
	v_readlane_b32 s82, v255, 26
	s_and_b64 s[8:9], s[0:1], s[8:9]
	v_readlane_b32 s89, v255, 18
	v_readlane_b32 s83, v255, 27
	s_mov_b32 s91, 0x1fffe0
	s_mov_b64 exec, s[8:9]
	s_cbranch_execz .LBB0_1065
	s_add_i32 s21, s6, 0
	v_mov_b32_e32 v2, s21
	s_load_dwordx2 s[4:5], s[4:5], 0xa8
	s_waitcnt vmcnt(0) expcnt(0) lgkmcnt(0)
	ds_read_b32 v4, v2 offset:32
	ds_read_b32 v2, v2 offset:36
	s_waitcnt lgkmcnt(1)
	v_cmp_ne_u32_e32 vcc, 0, v4
	s_cbranch_vccnz .LBB0_1027
	v_readlane_b32 s6, v255, 2
	v_readlane_b32 s7, v255, 3
	s_load_dwordx2 s[10:11], s[6:7], 0x4
	s_add_u32 s6, s4, 0x1000
	s_addc_u32 s7, s5, 0
	s_add_u32 s8, s4, 0x1100
	s_addc_u32 s9, s5, 0
	s_waitcnt lgkmcnt(0)
	s_mul_i32 s22, s10, s89
	s_add_u32 s10, s4, 0x1200
	s_mul_i32 s22, s22, s11
	s_addc_u32 s11, s5, 0
	s_add_u32 s12, s4, 0x1300
	s_addc_u32 s13, s5, 0
	s_mov_b32 s23, 1
	s_branch .LBB0_1015

; __device__ __forceinline__ unsigned xb_ld(unsigned* p)              { return __hip_atomic_load(p, __ATOMIC_RELAXED, __HIP_MEMORY_SCOPE_AGENT); }
; __device__ __forceinline__ unsigned xb_add(unsigned* p, unsigned v) { return __hip_atomic_fetch_add(p, v, __ATOMIC_RELAXED, __HIP_MEMORY_SCOPE_AGENT); }
; #define XB_SPIN(cond, bar) do { unsigned _sp = 0; while (cond) { __builtin_amdgcn_s_sleep(1); \
;     if ((++_sp & 255u) == 0u) { if (xb_ld(&(bar)[XB_TMO])) break; if (_sp > XB_SPIN_CAP) { atomicAdd(&(bar)[XB_TMO], 1u); break; } } } } while (0)
; __device__ __forceinline__ void xcd_barrier(const XcdBarrier& b, int local) {
;     ...
;         const unsigned old = xb_add(&bar[XB_XSUB(b.x)], 1u);
;         const unsigned gen = old / nloc;
;         if (old + 1u == (gen + 1u) * nloc) {
;             if (!local) {
;             __builtin_amdgcn_fence(__ATOMIC_RELEASE, "agent");
;             asm volatile("s_waitcnt vmcnt(0)" ::: "memory");
;             const unsigned og = xb_add(&bar[XB_TOP], 1u);
;             const unsigned tg = og / nx;
;             if (og + 1u == (tg + 1u) * nx) xb_add(&bar[XB_TOPGEN], 1u);
;             else XB_SPIN(xb_ld(&bar[XB_TOPGEN]) == tg, bar);
;             }
;             __builtin_amdgcn_fence(__ATOMIC_ACQUIRE, "agent");
;             xb_add(&bar[XB_XGEN(b.x)], 1u);
;             asm volatile("s_waitcnt vmcnt(0)" ::: "memory");
;         } else {
;             XB_SPIN(xb_ld(&bar[XB_XGEN(b.x)]) == gen, bar);
.LBB0_1029:
	s_or_b64 exec, exec, s[8:9]
	v_cvt_f32_u32_e32 v6, v4
	s_waitcnt vmcnt(0)
	v_readfirstlane_b32 s6, v5
	v_sub_u32_e32 v5, 0, v4
	v_rcp_iflag_f32_e32 v6, v6
	v_add_u32_e32 v7, s6, v3
	v_mul_f32_e32 v6, 0x4f7ffffe, v6
	v_cvt_u32_f32_e32 v6, v6
	v_mul_lo_u32 v3, v5, v6
	v_mul_hi_u32 v3, v6, v3
	v_add_u32_e32 v3, v6, v3
	v_mul_hi_u32 v3, v7, v3
	v_mul_lo_u32 v5, v3, v4
	v_sub_u32_e32 v5, v7, v5
	v_add_u32_e32 v6, 1, v3
	v_cmp_ge_u32_e32 vcc, v5, v4
	s_nop 1
	v_cndmask_b32_e32 v3, v3, v6, vcc
	v_sub_u32_e32 v6, v5, v4
	v_cndmask_b32_e32 v5, v5, v6, vcc
	v_add_u32_e32 v6, 1, v3
	v_cmp_ge_u32_e32 vcc, v5, v4
	v_add_u32_e32 v5, 1, v7
	s_nop 0
	v_cndmask_b32_e32 v3, v3, v6, vcc
	v_mul_lo_u32 v6, v4, v3
	v_add_u32_e32 v4, v6, v4
	v_cmp_ne_u32_e32 vcc, v5, v4
	s_and_saveexec_b64 s[6:7], vcc
	s_xor_b64 s[6:7], exec, s[6:7]
	s_cbranch_execz .LBB0_1043
	s_add_i32 s80, s24, 0x900
	s_lshl_b64 s[8:9], s[80:81], 2
	s_add_u32 s10, s4, s8
	s_addc_u32 s11, s5, s9
	s_cmp_eq_u32 s100, 0
	s_cbranch_scc1 .Lbi_a26775
	buffer_inv sc1
.Lbi_a26775:
	global_load_dword v0, v1, s[10:11] sc1
	s_waitcnt vmcnt(0)
	v_cmp_eq_u32_e32 vcc, v0, v3
	s_and_saveexec_b64 s[8:9], vcc
	s_cbranch_execz .LBB0_1042
	s_mov_b32 s22, 1
	s_mov_b64 s[12:13], 0
	s_branch .LBB0_1033

; __device__ __forceinline__ unsigned xb_add(unsigned* p, unsigned v) { return __hip_atomic_fetch_add(p, v, __ATOMIC_RELAXED, __HIP_MEMORY_SCOPE_AGENT); }
; __device__ __forceinline__ void xcd_barrier(const XcdBarrier& b, int local) {
;     ...
;         if (old + 1u == (gen + 1u) * nloc) {
;             if (!local) {
;             __builtin_amdgcn_fence(__ATOMIC_RELEASE, "agent");
;             asm volatile("s_waitcnt vmcnt(0)" ::: "memory");
;             const unsigned og = xb_add(&bar[XB_TOP], 1u);
;             const unsigned tg = og / nx;
;             if (og + 1u == (tg + 1u) * nx) xb_add(&bar[XB_TOPGEN], 1u);
.Lbi_b26775:
	s_waitcnt vmcnt(0)
.LBB0_1043:
	s_andn2_saveexec_b64 s[6:7], s[6:7]
	s_cbranch_execz .LBB0_1065
	v_cmp_ne_u32_e32 vcc, 0, v0
	s_cbranch_vccnz .LBB0_1062
	s_mov_b64 s[6:7], exec
	buffer_wbl2 sc1
	s_waitcnt lgkmcnt(0)
	s_waitcnt vmcnt(0)
	v_mbcnt_lo_u32_b32 v0, s6, 0
	v_mbcnt_hi_u32_b32 v0, s7, v0
	v_cmp_eq_u32_e32 vcc, 0, v0
	s_and_saveexec_b64 s[8:9], vcc
	s_cbranch_execz .LBB0_1047
	s_bcnt1_i32_b64 s6, s[6:7]
	v_mov_b32_e32 v3, s6
	v_mov_b32_e32 v4, 0x3000
	global_atomic_add v3, v4, v3, s[4:5] offset:1024 sc0

; __device__ __forceinline__ void xcd_barrier(const XcdBarrier& b, int local) {
;     asm volatile("s_waitcnt vmcnt(0)" ::: "memory");
;     __syncthreads();
;     if (threadIdx.x == 0) {
;         unsigned* bar = b.bar;
;         __builtin_amdgcn_s_waitcnt(0);
;         unsigned nloc = b.st[0], nx = b.st[1];
;         if (nloc == 0u) { xcd_barrier_complete(bar, b.x, nloc, nx); b.st[0] = nloc; b.st[1] = nx; }
.LBB0_1098:
	s_mov_b64 s[4:5], s[92:93]
	s_mov_b32 s6, 0x20000
	s_mov_b32 s0, 0x20000
	s_add_i32 s0, s0, 0
	v_mov_b32_e32 v0, s0
	ds_read_b32 v0, v0 offset:40
	s_mov_b32 s0, 0x20000
	s_add_i32 s0, s0, 0
	s_waitcnt lgkmcnt(0)
	v_readfirstlane_b32 s20, v0
	v_mov_b32_e32 v0, s0
	ds_read_b32 v0, v0 offset:48
	s_waitcnt vmcnt(0)
	s_waitcnt vmcnt(0) lgkmcnt(0)
	s_barrier
	v_readfirstlane_b32 s100, v0
	s_mov_b64 s[0:1], exec
	v_readlane_b32 s8, v255, 0
	v_readlane_b32 s9, v255, 1
	s_and_b64 s[8:9], s[0:1], s[8:9]
	s_mov_b64 exec, s[8:9]
	s_cbranch_execz .LBB0_1152
	s_add_i32 s21, s6, 0
	v_mov_b32_e32 v2, s21
	s_load_dwordx2 s[4:5], s[4:5], 0xa8
	s_waitcnt vmcnt(0) expcnt(0) lgkmcnt(0)
	ds_read_b32 v4, v2 offset:32
	ds_read_b32 v2, v2 offset:36
	s_waitcnt lgkmcnt(1)
	v_cmp_ne_u32_e32 vcc, 0, v4
	s_cbranch_vccnz .LBB0_1114
	v_readlane_b32 s6, v255, 2
	v_readlane_b32 s7, v255, 3
	s_load_dwordx2 s[10:11], s[6:7], 0x4
	s_add_u32 s6, s4, 0x1000
	s_addc_u32 s7, s5, 0
	s_add_u32 s8, s4, 0x1100
	s_addc_u32 s9, s5, 0
	s_waitcnt lgkmcnt(0)
	s_mul_i32 s22, s10, s89
	s_add_u32 s10, s4, 0x1200
	s_mul_i32 s22, s22, s11
	s_addc_u32 s11, s5, 0
	s_add_u32 s12, s4, 0x1300
	s_addc_u32 s13, s5, 0
	s_mov_b32 s23, 1
	s_branch .LBB0_1102

; __device__ __forceinline__ unsigned xb_add(unsigned* p, unsigned v) { return __hip_atomic_fetch_add(p, v, __ATOMIC_RELAXED, __HIP_MEMORY_SCOPE_AGENT); }
; __device__ __forceinline__ void xcd_barrier(const XcdBarrier& b, int local) {
;     ...
;         if (old + 1u == (gen + 1u) * nloc) {
;             if (!local) {
;             __builtin_amdgcn_fence(__ATOMIC_RELEASE, "agent");
;             asm volatile("s_waitcnt vmcnt(0)" ::: "memory");
;             const unsigned og = xb_add(&bar[XB_TOP], 1u);
;             const unsigned tg = og / nx;
;             if (og + 1u == (tg + 1u) * nx) xb_add(&bar[XB_TOPGEN], 1u);
.Lbi_b28842:
	s_waitcnt vmcnt(0)
.LBB0_1130:
	s_andn2_saveexec_b64 s[6:7], s[6:7]
	s_cbranch_execz .LBB0_1152
	v_cmp_ne_u32_e32 vcc, 0, v0
	s_cbranch_vccnz .LBB0_1149
	s_mov_b64 s[6:7], exec
	buffer_wbl2 sc1
	s_waitcnt lgkmcnt(0)
	s_waitcnt vmcnt(0)
	v_mbcnt_lo_u32_b32 v0, s6, 0
	v_mbcnt_hi_u32_b32 v0, s7, v0
	v_cmp_eq_u32_e32 vcc, 0, v0
	s_and_saveexec_b64 s[8:9], vcc
	s_cbranch_execz .LBB0_1134
	s_bcnt1_i32_b64 s6, s[6:7]
	v_mov_b32_e32 v3, s6
	v_mov_b32_e32 v4, 0x3000
	global_atomic_add v3, v4, v3, s[4:5] offset:1024 sc0

; __global__ void __launch_bounds__(512, 2) mega_fwd(Args a) {
	.amdhsa_kernel _Z8mega_fwd4Args
		.amdhsa_group_segment_fixed_size 0
		.amdhsa_private_segment_fixed_size 0
		.amdhsa_kernarg_size 432
		.amdhsa_user_sgpr_count 2
		.amdhsa_user_sgpr_dispatch_ptr 0
		.amdhsa_user_sgpr_queue_ptr 0
		.amdhsa_user_sgpr_kernarg_segment_ptr 1
		.amdhsa_user_sgpr_dispatch_id 0
		.amdhsa_user_sgpr_kernarg_preload_length 0
		.amdhsa_user_sgpr_kernarg_preload_offset 0
		.amdhsa_user_sgpr_private_segment_size 0
		.amdhsa_uses_dynamic_stack 0
		.amdhsa_enable_private_segment 0
		.amdhsa_system_sgpr_workgroup_id_x 1
		.amdhsa_system_sgpr_workgroup_id_y 0
		.amdhsa_system_sgpr_workgroup_id_z 0
		.amdhsa_system_sgpr_workgroup_info 0
		.amdhsa_system_vgpr_workitem_id 2
		.amdhsa_next_free_vgpr 256
		.amdhsa_next_free_sgpr 102
		.amdhsa_accum_offset 256
		.amdhsa_reserve_vcc 1
		.amdhsa_float_round_mode_32 0
		.amdhsa_float_round_mode_16_64 0
		.amdhsa_float_denorm_mode_32 3
		.amdhsa_float_denorm_mode_16_64 3
		.amdhsa_dx10_clamp 1
		.amdhsa_ieee_mode 1
		.amdhsa_fp16_overflow 0
		.amdhsa_tg_split 0
		.amdhsa_exception_fp_ieee_invalid_op 0
		.amdhsa_exception_fp_denorm_src 0
		.amdhsa_exception_fp_ieee_div_zero 0
		.amdhsa_exception_fp_ieee_overflow 0
		.amdhsa_exception_fp_ieee_underflow 0
		.amdhsa_exception_fp_ieee_inexact 0
		.amdhsa_exception_int_div_zero 0
	.end_amdhsa_kernel

; __global__ void __launch_bounds__(512, 2) mega_fwd(Args a) {
amdhsa.kernels:
  - .agpr_count:     0
    .args:
      - .offset:         0
        .size:           176
        .value_kind:     by_value
      - .offset:         176
        .size:           4
        .value_kind:     hidden_block_count_x
      - .offset:         180
        .size:           4
        .value_kind:     hidden_block_count_y
      - .offset:         184
        .size:           4
        .value_kind:     hidden_block_count_z
      - .offset:         188
        .size:           2
        .value_kind:     hidden_group_size_x
      - .offset:         190
        .size:           2
        .value_kind:     hidden_group_size_y
      - .offset:         192
        .size:           2
        .value_kind:     hidden_group_size_z
      - .offset:         194
        .size:           2
        .value_kind:     hidden_remainder_x
      - .offset:         196
        .size:           2
        .value_kind:     hidden_remainder_y
      - .offset:         198
        .size:           2
        .value_kind:     hidden_remainder_z
      - .offset:         216
        .size:           8
        .value_kind:     hidden_global_offset_x
      - .offset:         224
        .size:           8
        .value_kind:     hidden_global_offset_y
      - .offset:         232
        .size:           8
        .value_kind:     hidden_global_offset_z
      - .offset:         240
        .size:           2
        .value_kind:     hidden_grid_dims
      - .offset:         264
        .size:           8
        .value_kind:     hidden_multigrid_sync_arg
      - .offset:         296
        .size:           4
        .value_kind:     hidden_dynamic_lds_size
    .group_segment_fixed_size: 0
    .kernarg_segment_align: 8
    .kernarg_segment_size: 432
    .language:       OpenCL C
    .language_version:
      - 2
      - 0
    .max_flat_workgroup_size: 512
    .name:           _Z8mega_fwd4Args
    .private_segment_fixed_size: 0
    .sgpr_count:     108
    .sgpr_spill_count: 36
    .symbol:         _Z8mega_fwd4Args.kd
    .uniform_work_group_size: 1
    .uses_dynamic_stack: false
    .vgpr_count:     256
    .vgpr_spill_count: 0
    .wavefront_size: 64
